# GEMM-up epilogue LDS tile: XOR bank swizzle of the 16-byte column chunk with the row (writer and the four reader sites)
# speedup vs baseline: 1.0084x; 1.0076x over previous
; #define UFOR(v, n) _Pragma("unroll") for (int v = 0; v < (n); ++v)
; #define LDS_BARRIER() do { asm volatile("s_waitcnt lgkmcnt(0)" ::: "memory"); __builtin_amdgcn_s_barrier(); asm volatile("" ::: "memory"); } while (0)
; __device__ __forceinline__ unsigned pk2(float a, float b) { return (unsigned)f2bf(a) | ((unsigned)f2bf(b) << 16); }
; __device__ __forceinline__ float lo2f(unsigned u) { return __uint_as_float(u << 16); }
; __device__ __forceinline__ float hi2f(unsigned u) { return __uint_as_float(u & 0xffff0000u); }
; template <int EPI, int K, int KL> ...
;     ...
;     u16* U = (u16*)smem;
;     LDS_BARRIER();
;     UFOR(ai, 2) UFOR(bj, 2) UFOR(m, 4) {
;       const f32x4 a = acc[ai][bj][m][0], b = acc[ai][bj][m][1];
;       uint4 pk; pk.x = pk2(a[0], a[1]); pk.y = pk2(a[2], a[3]); pk.z = pk2(b[0], b[1]); pk.w = pk2(b[2], b[3]);
;       *(uint4*)(U + (ai * HALF + wr * 64 + m * 16 + fr) * 256 + bj * 128 + wc * 32 + fq * 8) = pk;
;     }
;     LDS_BARRIER();
;     {
;       const int c4 = (tid_ & 31) * 4, rb = tid_ >> 5;
;       const int gc = pn * 128 + c4;
;       float wg[4][3], wv[4][3];
;       UFOR(q, 4) UFOR(x, 3) { wg[q][x] = e.cw[(size_t)(gc + q) * 3 + x]; wv[q][x] = e.cw[(size_t)(DFF + gc + q) * 3 + x]; }
;       float pg[4], cgv[4], ng[4], pvv[4], cv[4], nv[4];
;       const int lr0 = rb * 16;
;       {
;         const int lrp = lr0 > 0 ? lr0 - 1 : 0;
;         const uint2 a = *(const uint2*)(U + lrp * 256 + c4), b = *(const uint2*)(U + lrp * 256 + 128 + c4);
;         pg[0] = lo2f(a.x); pg[1] = hi2f(a.x); pg[2] = lo2f(a.y); pg[3] = hi2f(a.y);
;         pvv[0] = lo2f(b.x); pvv[1] = hi2f(b.x); pvv[2] = lo2f(b.y); pvv[3] = hi2f(b.y);
;         const uint2 c = *(const uint2*)(U + lr0 * 256 + c4), d = *(const uint2*)(U + lr0 * 256 + 128 + c4);
;         cgv[0] = lo2f(c.x); cgv[1] = hi2f(c.x); cgv[2] = lo2f(c.y); cgv[3] = hi2f(c.y);
;         cv[0] = lo2f(d.x); cv[1] = hi2f(d.x); cv[2] = lo2f(d.y); cv[3] = hi2f(d.y);
;       }
.LBB0_1110:
	s_or_b64 exec, exec, s[40:41]
	v_bfe_u32 v128, v152, 4, 4
	v_xor_b32_e32 v128, v128, v154
	v_lshlrev_b32_e32 v128, 4, v128
	v_lshlrev_b32_e32 v129, 15, v153
	v_lshlrev_b32_e32 v130, 9, v154
	v_add3_u32 v128, v128, v129, v130
	v_cvt_pk_bf16_f32 v124, v124, v125
	v_cvt_pk_bf16_f32 v125, v126, v127
	v_cvt_pk_bf16_f32 v126, v120, v121
	v_cvt_pk_bf16_f32 v116, v116, v117
	v_cvt_pk_bf16_f32 v117, v118, v119
	v_cvt_pk_bf16_f32 v118, v112, v113
	v_cvt_pk_bf16_f32 v108, v108, v109
	v_cvt_pk_bf16_f32 v109, v110, v111
	v_cvt_pk_bf16_f32 v110, v104, v105
	v_cvt_pk_bf16_f32 v100, v100, v101
	v_cvt_pk_bf16_f32 v101, v102, v103
	v_cvt_pk_bf16_f32 v102, v96, v97
	v_cvt_pk_bf16_f32 v92, v92, v93
	v_cvt_pk_bf16_f32 v93, v94, v95
	v_cvt_pk_bf16_f32 v94, v88, v89
	v_cvt_pk_bf16_f32 v84, v84, v85
	v_cvt_pk_bf16_f32 v85, v86, v87
	v_cvt_pk_bf16_f32 v86, v80, v81
	v_cvt_pk_bf16_f32 v76, v76, v77
	v_cvt_pk_bf16_f32 v77, v78, v79
	v_cvt_pk_bf16_f32 v78, v72, v73
	v_cvt_pk_bf16_f32 v68, v68, v69
	v_cvt_pk_bf16_f32 v69, v70, v71
	v_cvt_pk_bf16_f32 v70, v64, v65
	v_cvt_pk_bf16_f32 v71, v66, v67
	v_cvt_pk_bf16_f32 v60, v60, v61
	v_cvt_pk_bf16_f32 v61, v62, v63
	v_cvt_pk_bf16_f32 v62, v56, v57
	v_cvt_pk_bf16_f32 v63, v58, v59
	v_cvt_pk_bf16_f32 v52, v52, v53
	v_cvt_pk_bf16_f32 v53, v54, v55
	v_cvt_pk_bf16_f32 v54, v48, v49
	v_cvt_pk_bf16_f32 v55, v50, v51
	v_cvt_pk_bf16_f32 v44, v44, v45
	v_cvt_pk_bf16_f32 v45, v46, v47
	v_cvt_pk_bf16_f32 v46, v40, v41
	v_cvt_pk_bf16_f32 v47, v42, v43
	v_cvt_pk_bf16_f32 v36, v36, v37
	v_cvt_pk_bf16_f32 v37, v38, v39
	v_cvt_pk_bf16_f32 v38, v32, v33
	v_cvt_pk_bf16_f32 v39, v34, v35
	v_cvt_pk_bf16_f32 v28, v28, v29
	v_cvt_pk_bf16_f32 v29, v30, v31
	v_cvt_pk_bf16_f32 v30, v24, v25
	v_cvt_pk_bf16_f32 v31, v26, v27
	v_cvt_pk_bf16_f32 v20, v20, v21
	v_cvt_pk_bf16_f32 v21, v22, v23
	v_cvt_pk_bf16_f32 v22, v16, v17
	v_cvt_pk_bf16_f32 v23, v18, v19
	v_cvt_pk_bf16_f32 v12, v12, v13
	v_cvt_pk_bf16_f32 v13, v14, v15
	v_cvt_pk_bf16_f32 v14, v8, v9
	v_cvt_pk_bf16_f32 v15, v10, v11
	v_cvt_pk_bf16_f32 v4, v4, v5
	v_cvt_pk_bf16_f32 v5, v6, v7
	v_cvt_pk_bf16_f32 v127, v122, v123
	v_cvt_pk_bf16_f32 v119, v114, v115
	v_cvt_pk_bf16_f32 v111, v106, v107
	v_cvt_pk_bf16_f32 v103, v98, v99
	v_cvt_pk_bf16_f32 v95, v90, v91
	v_cvt_pk_bf16_f32 v87, v82, v83
	v_cvt_pk_bf16_f32 v79, v74, v75
	v_cvt_pk_bf16_f32 v7, v2, v3
	v_cvt_pk_bf16_f32 v6, v0, v1
	v_add_u32_e32 v16, 0x14100, v128
	s_waitcnt lgkmcnt(0)
	s_barrier
	v_add_u32_e32 v32, 0x10100, v128
	ds_write_b128 v16, v[12:15]
	v_and_b32_e32 v16, 0x7c, v132
	v_add_u32_e32 v64, 0x10000, v128
	v_add_u32_e32 v56, 0x12000, v128
	v_add_u32_e32 v48, 0x14000, v128
	v_add_u32_e32 v40, 0x16000, v128
	ds_write_b128 v32, v[28:31]
	v_add_u32_e32 v24, 0x12100, v128
	v_add_u32_e32 v8, 0x16100, v128
	v_lshl_or_b32 v32, s51, 7, v16
	ds_write_b128 v128, v[124:127]
	ds_write_b128 v128, v[116:119] offset:8192
	ds_write_b128 v128, v[108:111] offset:16384
	ds_write_b128 v128, v[100:103] offset:24576
	ds_write_b128 v128, v[92:95] offset:256
	ds_write_b128 v128, v[84:87] offset:8448
	ds_write_b128 v128, v[76:79] offset:16640
	ds_write_b128 v128, v[68:71] offset:24832
	ds_write_b128 v64, v[60:63]
	ds_write_b128 v56, v[52:55]
	ds_write_b128 v48, v[44:47]
	ds_write_b128 v40, v[36:39]
	ds_write_b128 v24, v[20:23]
	ds_write_b128 v8, v[4:7]
	v_add_u32_e32 v0, 0x1600, v32
	s_waitcnt lgkmcnt(0)
	s_barrier
	v_mad_i64_i32 v[4:5], s[40:41], v0, 12, s[46:47]
	v_mad_i64_i32 v[12:13], s[40:41], v32, 12, s[46:47]
	global_load_dwordx4 v[24:27], v[4:5], off offset:16
	global_load_dwordx4 v[0:3], v[4:5], off offset:32
	s_nop 0
	global_load_dwordx4 v[4:7], v[4:5], off
	s_nop 0
	global_load_dwordx4 v[8:11], v[12:13], off offset:16
	global_load_dwordx4 v[28:31], v[12:13], off offset:32
	s_nop 0
	global_load_dwordx4 v[12:15], v[12:13], off
	v_ashrrev_i32_e32 v34, 1, v152
	v_and_b32_e32 v132, -16, v34
	v_mov_b32_e32 v17, 0xffffff00
	v_lshl_add_u32 v17, v132, 8, v17
	v_cmp_lt_i32_e32 vcc, 15, v34
	v_lshl_add_u32 v64, v16, 1, 0
	v_bfe_u32 v96, v152, 1, 4
	v_and_b32_e32 v97, 1, v152
	v_lshlrev_b32_e32 v97, 3, v97
	s_ashr_i32 s51, s50, 31
	v_cndmask_b32_e32 v17, 0, v17, vcc
	v_lshrrev_b32_e32 v98, 8, v17
	v_and_b32_e32 v98, 15, v98
	v_xor_b32_e32 v98, v98, v96
	v_lshl_add_u32 v98, v98, 4, v97
	v_lshl_add_u32 v16, v17, 1, v98
	ds_read2_b64 v[16:19], v16 offset1:32
	s_ashr_i32 s53, s52, 31
	s_add_u32 s56, s52, -1
	s_addc_u32 s57, s53, -1
	s_add_i32 s61, s52, -1
	s_waitcnt lgkmcnt(0)
	v_and_b32_e32 v56, 0xffff0000, v16
	v_lshlrev_b32_e32 v58, 16, v16
	v_lshl_add_u32 v98, v96, 4, v97
	v_lshl_add_u32 v16, v132, 9, v98
	ds_read2_b64 v[20:23], v16 offset1:32
	s_ashr_i32 s62, s61, 31
	v_ashrrev_i32_e32 v33, 31, v32
	v_cmp_lt_i32_e64 s[40:41], -1, v34
	s_sub_u32 s58, s50, s42
	v_ashrrev_i32_e32 v35, 31, v132
	v_mov_b32_e32 v34, v132
	s_waitcnt lgkmcnt(0)
	v_lshlrev_b32_e32 v47, 16, v21
	v_lshlrev_b32_e32 v46, 16, v20
	v_and_b32_e32 v45, 0xffff0000, v21
	v_and_b32_e32 v44, 0xffff0000, v20
	v_lshlrev_b32_e32 v50, 16, v22
	v_lshlrev_b32_e32 v51, 16, v23
	v_and_b32_e32 v49, 0xffff0000, v23
	v_and_b32_e32 v48, 0xffff0000, v22
	s_subb_u32 s59, s51, s43
	s_movk_i32 s63, 0x2c00
	v_lshlrev_b32_e32 v63, 16, v19
	v_lshlrev_b32_e32 v62, 16, v18
	v_and_b32_e32 v61, 0xffff0000, v19
	v_and_b32_e32 v60, 0xffff0000, v18
	v_and_b32_e32 v57, 0xffff0000, v17
	v_lshlrev_b32_e32 v59, 16, v17
	v_mov_b32_e32 v248, 0x3a27c5ac
	s_waitcnt vmcnt(0)
	v_mov_b32_e32 v16, v24
	v_mov_b32_e32 v20, v9
	v_mov_b32_e32 v21, v31
	v_mov_b32_e32 v9, v30
	v_mov_b32_e32 v22, v15
	v_mov_b32_e32 v23, v29
	v_mov_b32_e32 v15, v28
	v_lshl_add_u64 v[28:29], s[42:43], 0, v[34:35]
	v_lshlrev_b64 v[30:31], 1, v[32:33]
	v_mov_b32_e32 v18, v7
	v_mov_b32_e32 v19, v1
	v_mov_b32_e32 v7, v0
	v_mov_b32_e32 v0, v13
	v_mov_b32_e32 v1, v11
	v_mov_b32_e32 v13, v10
	v_mov_b32_e32 v11, s59
	v_sub_co_u32_e32 v10, vcc, s58, v132
	v_mad_u64_u32 v[30:31], s[58:59], v28, s63, v[30:31]
	v_mov_b32_e32 v32, v31
	s_sub_u32 s42, s61, s42
	v_subb_co_u32_e32 v11, vcc, v11, v35, vcc
	v_mad_u64_u32 v[32:33], s[58:59], v29, s63, v[32:33]
	s_subb_u32 s43, s62, s43
	v_mov_b32_e32 v31, v32
	v_readlane_b32 s58, v254, 38
	v_mov_b32_e32 v33, s43
	v_sub_co_u32_e32 v32, vcc, s42, v132
	v_readlane_b32 s59, v254, 39
	s_nop 0
	v_subb_co_u32_e32 v33, vcc, v33, v35, vcc
	v_mov_b32_e32 v17, v2
	v_mov_b32_e32 v2, v25
	v_mov_b32_e32 v24, v5
	v_mov_b32_e32 v25, v27
	v_mov_b32_e32 v5, v26
	v_lshl_add_u64 v[26:27], v[10:11], 0, -1
	v_lshl_add_u64 v[30:31], s[58:59], 0, v[30:31]
	v_lshl_add_u64 v[34:35], v[32:33], 0, -1
	s_mov_b64 s[58:59], 0
	s_branch .LBB0_1112

; #define UFOR(v, n) _Pragma("unroll") for (int v = 0; v < (n); ++v)
; __device__ __forceinline__ unsigned pk2(float a, float b) { return (unsigned)f2bf(a) | ((unsigned)f2bf(b) << 16); }
; __device__ __forceinline__ float lo2f(unsigned u) { return __uint_as_float(u << 16); }
; __device__ __forceinline__ float hi2f(unsigned u) { return __uint_as_float(u & 0xffff0000u); }
; __device__ __forceinline__ float siluf_(float x) { return x / (1.f + __expf(-x)); }
; template <int EPI, int K, int KL> ...
;     ...
;       for (int q = 0; q < 16; ++q) {
;         const int lr = lr0 + q;
;         const int lrn = lr < 255 ? lr + 1 : 255;
;         const uint2 a = *(const uint2*)(U + lrn * 256 + c4), b = *(const uint2*)(U + lrn * 256 + 128 + c4);
;         ng[0] = lo2f(a.x); ng[1] = hi2f(a.x); ng[2] = lo2f(a.y); ng[3] = hi2f(a.y);
;         nv[0] = lo2f(b.x); nv[1] = hi2f(b.x); nv[2] = lo2f(b.y); nv[3] = hi2f(b.y);
;         const long gr = brow + lr;
;         const bool valid = (gr >= seq0) && (gr < seq1) && (lr >= 1 || gr == seq0) && (lr <= 254 || gr == seq1 - 1);
;         if (valid) {
;           const float mp = (gr - 1 >= seq0) ? 1.f : 0.f, mn = (gr + 1 < seq1) ? 1.f : 0.f;
;           float o[4];
;           UFOR(x, 4) {
;             const float g = wg[x][0] * pg[x] * mp + wg[x][1] * cgv[x] + wg[x][2] * ng[x] * mn;
;             const float v = wv[x][0] * pvv[x] * mp + wv[x][1] * cv[x] + wv[x][2] * nv[x] * mn;
;             o[x] = siluf_(g) * v;
;           }
;           uint2 pk; pk.x = pk2(o[0], o[1]); pk.y = pk2(o[2], o[3]);
;           *(uint2*)(e.h2 + (size_t)gr * DFF + gc) = pk;
.LBB0_1112:
	v_lshl_add_u64 v[52:53], v[132:133], 0, s[58:59]
	v_min_i32_e32 v36, 0xfe, v52
	v_add_u32_e32 v98, 1, v36
	v_and_b32_e32 v99, 15, v98
	v_xor_b32_e32 v99, v99, v96
	v_lshl_add_u32 v99, v99, 4, v97
	v_lshl_add_u32 v36, v98, 9, v99
	v_lshl_add_u64 v[54:55], v[28:29], 0, s[58:59]
	ds_read2_b64 v[40:43], v36 offset1:32
	v_cmp_le_i64_e32 vcc, s[50:51], v[54:55]
	v_cmp_gt_i64_e64 s[42:43], s[52:53], v[54:55]
	s_and_b64 s[62:63], vcc, s[42:43]
	v_cmp_lt_i32_e32 vcc, 0, v52
	v_cmp_eq_u64_e64 s[42:43], s[58:59], v[10:11]
	s_or_b64 s[42:43], vcc, s[42:43]
	s_and_b64 s[62:63], s[62:63], s[42:43]
	v_cmp_gt_i32_e32 vcc, s27, v52
	v_cmp_eq_u64_e64 s[42:43], s[58:59], v[32:33]
	s_or_b64 s[42:43], vcc, s[42:43]
	s_waitcnt lgkmcnt(0)
	v_lshlrev_b32_e32 v36, 16, v40
	v_lshlrev_b32_e32 v37, 16, v41
	v_and_b32_e32 v39, 0xffff0000, v41
	v_and_b32_e32 v38, 0xffff0000, v40
	v_lshlrev_b32_e32 v40, 16, v42
	v_lshlrev_b32_e32 v41, 16, v43
	v_and_b32_e32 v43, 0xffff0000, v43
	v_and_b32_e32 v42, 0xffff0000, v42
	s_and_b64 s[62:63], s[62:63], s[42:43]
	s_and_saveexec_b64 s[42:43], s[62:63]
	s_cbranch_execz .LBB0_1114
	v_cmp_lt_i64_e32 vcc, s[50:51], v[54:55]
	v_pk_mul_f32 v[58:59], v[12:13], v[58:59]
	v_pk_mul_f32 v[56:57], v[22:23], v[56:57]
	v_cndmask_b32_e64 v66, 0, 1.0, vcc
	v_cmp_gt_i64_e32 vcc, s[56:57], v[54:55]
	v_pk_mul_f32 v[58:59], v[58:59], v[66:67] op_sel_hi:[1,0]
	v_pk_mul_f32 v[70:71], v[14:15], v[36:37]
	v_cndmask_b32_e64 v68, 0, 1.0, vcc
	v_pk_fma_f32 v[58:59], v[0:1], v[46:47], v[58:59]
	v_pk_mul_f32 v[56:57], v[56:57], v[66:67] op_sel_hi:[1,0]
	v_pk_mul_f32 v[74:75], v[20:21], v[38:39]
	v_pk_fma_f32 v[58:59], v[70:71], v[68:69], v[58:59] op_sel_hi:[1,0,1]
	v_pk_fma_f32 v[56:57], v[8:9], v[44:45], v[56:57]
	v_mul_f32_e32 v53, 0xbfb8aa3b, v58
	v_pk_fma_f32 v[56:57], v[74:75], v[68:69], v[56:57] op_sel_hi:[1,0,1]
	v_exp_f32_e32 v70, v53
	v_mul_f32_e32 v53, 0xbfb8aa3b, v56
	v_exp_f32_e32 v74, v53
	v_mul_f32_e32 v53, 0xbfb8aa3b, v59
	v_exp_f32_e32 v71, v53
	v_pk_mul_f32 v[62:63], v[4:5], v[62:63]
	v_pk_mul_f32 v[72:73], v[6:7], v[40:41]
	v_pk_mul_f32 v[62:63], v[62:63], v[66:67] op_sel_hi:[1,0]
	v_pk_add_f32 v[70:71], v[70:71], 1.0 op_sel_hi:[1,0]
	v_pk_fma_f32 v[62:63], v[24:25], v[50:51], v[62:63]
	v_pk_fma_f32 v[62:63], v[68:69], v[72:73], v[62:63] op_sel_hi:[0,1,1]
	v_pk_mul_f32 v[60:61], v[18:19], v[60:61]
	v_pk_mul_f32 v[76:77], v[2:3], v[42:43]
	s_nop 0
	v_div_scale_f32 v80, vcc, v70, v70, v58
	v_div_scale_f32 v81, vcc, v71, v71, v59
	v_rcp_f32_e32 v82, v80
	v_rcp_f32_e32 v83, v81
	v_div_scale_f32 v86, s[62:63], v58, v70, v58
	v_div_scale_f32 v87, vcc, v59, v71, v59
	v_pk_fma_f32 v[84:85], v[80:81], v[82:83], 1.0 op_sel_hi:[1,1,0] neg_lo:[1,0,0] neg_hi:[1,0,0]
	v_pk_fma_f32 v[82:83], v[84:85], v[82:83], v[82:83]
	v_pk_mul_f32 v[88:89], v[86:87], v[82:83]
	v_pk_fma_f32 v[84:85], v[80:81], v[88:89], v[86:87] neg_lo:[1,0,0] neg_hi:[1,0,0]
	v_pk_fma_f32 v[88:89], v[84:85], v[82:83], v[88:89]
	v_pk_fma_f32 v[84:85], v[80:81], v[88:89], v[86:87] neg_lo:[1,0,0] neg_hi:[1,0,0]
	v_div_fmas_f32 v85, v85, v83, v89
	s_mov_b64 vcc, s[62:63]
	s_nop 0
	v_div_fmas_f32 v84, v84, v82, v88
	v_div_fixup_f32 v59, v85, v71, v59
	v_div_fixup_f32 v58, v84, v70, v58
	v_mul_f32_e32 v53, 0xbfb8aa3b, v57
	v_exp_f32_e32 v75, v53
	v_pk_mul_f32 v[58:59], v[62:63], v[58:59]
	v_pk_mul_f32 v[60:61], v[60:61], v[66:67] op_sel_hi:[1,0]
	v_pk_add_f32 v[62:63], v[74:75], 1.0 op_sel_hi:[1,0]
	s_nop 0
	v_pk_fma_f32 v[60:61], v[16:17], v[48:49], v[60:61]
	v_pk_fma_f32 v[60:61], v[68:69], v[76:77], v[60:61] op_sel_hi:[0,1,1]
	s_nop 0
	v_div_scale_f32 v80, vcc, v62, v62, v56
	v_div_scale_f32 v81, vcc, v63, v63, v57
	v_rcp_f32_e32 v82, v80
	v_rcp_f32_e32 v83, v81
	v_div_scale_f32 v86, s[62:63], v56, v62, v56
	v_div_scale_f32 v87, vcc, v57, v63, v57
	v_pk_fma_f32 v[84:85], v[80:81], v[82:83], 1.0 op_sel_hi:[1,1,0] neg_lo:[1,0,0] neg_hi:[1,0,0]
	v_pk_fma_f32 v[82:83], v[84:85], v[82:83], v[82:83]
	v_pk_mul_f32 v[88:89], v[86:87], v[82:83]
	v_pk_fma_f32 v[84:85], v[80:81], v[88:89], v[86:87] neg_lo:[1,0,0] neg_hi:[1,0,0]
	v_pk_fma_f32 v[88:89], v[84:85], v[82:83], v[88:89]
	v_pk_fma_f32 v[84:85], v[80:81], v[88:89], v[86:87] neg_lo:[1,0,0] neg_hi:[1,0,0]
	v_div_fmas_f32 v85, v85, v83, v89
	s_mov_b64 vcc, s[62:63]
	s_nop 0
	v_div_fmas_f32 v84, v84, v82, v88
	v_div_fixup_f32 v57, v85, v63, v57
	v_div_fixup_f32 v56, v84, v62, v56
	v_pk_mul_f32 v[56:57], v[60:61], v[56:57]
	v_cvt_pk_bf16_f32 v56, v58, v56
	v_cvt_pk_bf16_f32 v57, v59, v57
	v_add_co_u32_e32 v58, vcc, 0xffffe000, v30
	s_nop 1
	v_addc_co_u32_e32 v59, vcc, -1, v31, vcc
	global_store_dwordx2 v[58:59], v[56:57], off offset:-3072
; #define UFOR(v, n) _Pragma("unroll") for (int v = 0; v < (n); ++v)
; __device__ __forceinline__ unsigned pk2(float a, float b) { return (unsigned)f2bf(a) | ((unsigned)f2bf(b) << 16); }
; __device__ __forceinline__ float lo2f(unsigned u) { return __uint_as_float(u << 16); }
; __device__ __forceinline__ float hi2f(unsigned u) { return __uint_as_float(u & 0xffff0000u); }
; __device__ __forceinline__ float siluf_(float x) { return x / (1.f + __expf(-x)); }
; template <int EPI, int K, int KL> ...
;     ...
;       for (int q = 0; q < 16; ++q) {
;         const int lr = lr0 + q;
;         const int lrn = lr < 255 ? lr + 1 : 255;
;         const uint2 a = *(const uint2*)(U + lrn * 256 + c4), b = *(const uint2*)(U + lrn * 256 + 128 + c4);
;         ng[0] = lo2f(a.x); ng[1] = hi2f(a.x); ng[2] = lo2f(a.y); ng[3] = hi2f(a.y);
;         nv[0] = lo2f(b.x); nv[1] = hi2f(b.x); nv[2] = lo2f(b.y); nv[3] = hi2f(b.y);
;         const long gr = brow + lr;
;         const bool valid = (gr >= seq0) && (gr < seq1) && (lr >= 1 || gr == seq0) && (lr <= 254 || gr == seq1 - 1);
;         if (valid) {
;           const float mp = (gr - 1 >= seq0) ? 1.f : 0.f, mn = (gr + 1 < seq1) ? 1.f : 0.f;
;           float o[4];
;           UFOR(x, 4) {
;             const float g = wg[x][0] * pg[x] * mp + wg[x][1] * cgv[x] + wg[x][2] * ng[x] * mn;
;             const float v = wv[x][0] * pvv[x] * mp + wv[x][1] * cv[x] + wv[x][2] * nv[x] * mn;
;             o[x] = siluf_(g) * v;
;           }
;           uint2 pk; pk.x = pk2(o[0], o[1]); pk.y = pk2(o[2], o[3]);
;           *(uint2*)(e.h2 + (size_t)gr * DFF + gc) = pk;
;         }
;         UFOR(x, 4) { pg[x] = cgv[x]; cgv[x] = ng[x]; pvv[x] = cv[x]; cv[x] = nv[x]; }
.LBB0_1114:
	s_or_b64 exec, exec, s[42:43]
	v_add_u32_e32 v62, 1, v52
	v_min_i32_e32 v52, 0xfe, v62
	v_add_u32_e32 v98, 1, v52
	v_and_b32_e32 v99, 15, v98
	v_xor_b32_e32 v99, v99, v96
	v_lshl_add_u32 v99, v99, 4, v97
	v_lshl_add_u32 v52, v98, 9, v99
	v_lshl_add_u64 v[54:55], v[54:55], 0, 1
	ds_read2_b64 v[58:61], v52 offset1:32
	v_cmp_le_i64_e32 vcc, s[50:51], v[54:55]
	v_cmp_gt_i64_e64 s[42:43], s[52:53], v[54:55]
	s_and_b64 s[42:43], vcc, s[42:43]
	v_cmp_eq_u64_e32 vcc, s[58:59], v[26:27]
	s_or_b64 s[62:63], s[40:41], vcc
	s_and_b64 s[62:63], s[42:43], s[62:63]
	v_cmp_gt_i32_e32 vcc, s27, v62
	v_cmp_eq_u64_e64 s[42:43], s[58:59], v[34:35]
	s_or_b64 s[42:43], vcc, s[42:43]
	s_waitcnt lgkmcnt(0)
	v_lshlrev_b32_e32 v52, 16, v58
	v_lshlrev_b32_e32 v53, 16, v59
	v_and_b32_e32 v57, 0xffff0000, v59
	v_and_b32_e32 v56, 0xffff0000, v58
	v_lshlrev_b32_e32 v58, 16, v60
	v_lshlrev_b32_e32 v59, 16, v61
	v_and_b32_e32 v61, 0xffff0000, v61
	v_and_b32_e32 v60, 0xffff0000, v60
	s_and_b64 s[62:63], s[62:63], s[42:43]
	s_and_saveexec_b64 s[42:43], s[62:63]
	s_cbranch_execz .LBB0_1111
	v_cmp_lt_i64_e32 vcc, s[50:51], v[54:55]
	v_pk_mul_f32 v[46:47], v[12:13], v[46:47]
	v_pk_mul_f32 v[66:67], v[14:15], v[52:53]
	v_cndmask_b32_e64 v62, 0, 1.0, vcc
	v_cmp_gt_i64_e32 vcc, s[56:57], v[54:55]
	v_pk_mul_f32 v[46:47], v[46:47], v[62:63] op_sel_hi:[1,0]
	v_pk_mul_f32 v[44:45], v[22:23], v[44:45]
	v_cndmask_b32_e64 v54, 0, 1.0, vcc
	v_pk_fma_f32 v[46:47], v[0:1], v[36:37], v[46:47]
	v_pk_mul_f32 v[44:45], v[44:45], v[62:63] op_sel_hi:[1,0]
	v_pk_fma_f32 v[46:47], v[66:67], v[54:55], v[46:47] op_sel_hi:[1,0,1]
	v_pk_mul_f32 v[50:51], v[4:5], v[50:51]
	v_pk_mul_f32 v[70:71], v[20:21], v[56:57]
	v_mul_f32_e32 v55, 0xbfb8aa3b, v46
	v_pk_fma_f32 v[44:45], v[8:9], v[38:39], v[44:45]
	v_pk_mul_f32 v[50:51], v[50:51], v[62:63] op_sel_hi:[1,0]
	v_pk_fma_f32 v[44:45], v[70:71], v[54:55], v[44:45] op_sel_hi:[1,0,1]
	v_pk_mul_f32 v[68:69], v[6:7], v[58:59]
	v_exp_f32_e32 v66, v55
	v_mul_f32_e32 v55, 0xbfb8aa3b, v44
	v_pk_fma_f32 v[50:51], v[24:25], v[40:41], v[50:51]
	v_exp_f32_e32 v70, v55
	v_pk_fma_f32 v[50:51], v[54:55], v[68:69], v[50:51] op_sel_hi:[0,1,1]
	v_mul_f32_e32 v55, 0xbfb8aa3b, v47
	v_exp_f32_e32 v67, v55
	v_pk_mul_f32 v[48:49], v[18:19], v[48:49]
	v_pk_mul_f32 v[72:73], v[2:3], v[60:61]
	v_pk_add_f32 v[66:67], v[66:67], 1.0 op_sel_hi:[1,0]
	s_nop 0
	s_nop 0
	s_nop 0
	v_div_scale_f32 v80, vcc, v66, v66, v46
	v_div_scale_f32 v81, vcc, v67, v67, v47
	v_rcp_f32_e32 v82, v80
	v_rcp_f32_e32 v83, v81
	v_div_scale_f32 v86, s[62:63], v46, v66, v46
	v_div_scale_f32 v87, vcc, v47, v67, v47
	v_pk_fma_f32 v[84:85], v[80:81], v[82:83], 1.0 op_sel_hi:[1,1,0] neg_lo:[1,0,0] neg_hi:[1,0,0]
	v_pk_fma_f32 v[82:83], v[84:85], v[82:83], v[82:83]
	v_pk_mul_f32 v[88:89], v[86:87], v[82:83]
	v_pk_fma_f32 v[84:85], v[80:81], v[88:89], v[86:87] neg_lo:[1,0,0] neg_hi:[1,0,0]
	v_pk_fma_f32 v[88:89], v[84:85], v[82:83], v[88:89]
	v_pk_fma_f32 v[84:85], v[80:81], v[88:89], v[86:87] neg_lo:[1,0,0] neg_hi:[1,0,0]
	v_div_fmas_f32 v85, v85, v83, v89
	s_mov_b64 vcc, s[62:63]
	s_nop 0
	v_div_fmas_f32 v84, v84, v82, v88
	v_div_fixup_f32 v47, v85, v67, v47
	v_div_fixup_f32 v46, v84, v66, v46
	v_pk_mul_f32 v[46:47], v[50:51], v[46:47]
	v_mul_f32_e32 v50, 0xbfb8aa3b, v45
	v_exp_f32_e32 v71, v50
	v_pk_mul_f32 v[48:49], v[48:49], v[62:63] op_sel_hi:[1,0]
	v_pk_add_f32 v[50:51], v[70:71], 1.0 op_sel_hi:[1,0]
	v_pk_fma_f32 v[48:49], v[16:17], v[42:43], v[48:49]
	s_nop 0
	v_pk_fma_f32 v[48:49], v[54:55], v[72:73], v[48:49] op_sel_hi:[0,1,1]
	s_nop 0
	s_nop 0
	v_div_scale_f32 v80, vcc, v50, v50, v44
	v_div_scale_f32 v81, vcc, v51, v51, v45
	v_rcp_f32_e32 v82, v80
	v_rcp_f32_e32 v83, v81
	v_div_scale_f32 v86, s[62:63], v44, v50, v44
	v_div_scale_f32 v87, vcc, v45, v51, v45
	v_pk_fma_f32 v[84:85], v[80:81], v[82:83], 1.0 op_sel_hi:[1,1,0] neg_lo:[1,0,0] neg_hi:[1,0,0]
	v_pk_fma_f32 v[82:83], v[84:85], v[82:83], v[82:83]
	v_pk_mul_f32 v[88:89], v[86:87], v[82:83]
	v_pk_fma_f32 v[84:85], v[80:81], v[88:89], v[86:87] neg_lo:[1,0,0] neg_hi:[1,0,0]
	v_pk_fma_f32 v[88:89], v[84:85], v[82:83], v[88:89]
	v_pk_fma_f32 v[84:85], v[80:81], v[88:89], v[86:87] neg_lo:[1,0,0] neg_hi:[1,0,0]
	v_div_fmas_f32 v85, v85, v83, v89
	s_mov_b64 vcc, s[62:63]
	s_nop 0
	v_div_fmas_f32 v84, v84, v82, v88
	v_div_fixup_f32 v45, v85, v51, v45
	v_div_fixup_f32 v44, v84, v50, v44
	v_pk_mul_f32 v[44:45], v[48:49], v[44:45]
	v_cvt_pk_bf16_f32 v45, v47, v45
	v_cvt_pk_bf16_f32 v44, v46, v44
	global_store_dwordx2 v[30:31], v[44:45], off
	s_branch .LBB0_1111
